# MLA row-max: 17 v_max3 instead of 52 canonicalising max ops
# speedup vs baseline: 1.0063x; 1.0063x over previous
.LBB0_989:
	s_bitcmp1_b32 s36, 0
	s_cselect_b32 s17, 0xac00, 0
	s_add_i32 s31, s17, 0
	s_ashr_i32 s17, s16, 31
	s_mul_i32 s36, s16, 0x600
	s_mul_hi_i32 s37, s16, 0x600
	s_add_u32 s36, s15, s36
	s_addc_u32 s37, s25, s37
	v_lshl_add_u64 v[66:67], v[0:1], 1, s[36:37]
	v_add_co_u32_e32 v68, vcc, s47, v66
	s_lshl_b64 s[16:17], s[16:17], 7
	s_nop 0
	v_addc_co_u32_e32 v69, vcc, 0, v67, vcc
	global_load_dwordx4 v[146:149], v[66:67], off
	global_load_dwordx4 v[154:157], v[68:69], off
	v_lshl_add_u64 v[66:67], v[184:185], 0, s[16:17]
	s_mov_b32 s16, 0x88000
	global_load_dwordx4 v[158:161], v[66:67], off
	global_load_dwordx4 v[150:153], v[186:187], off
	v_add_co_u32_e32 v66, vcc, s16, v186
	v_add_u32_e32 v206, s31, v202
	s_nop 0
	v_addc_co_u32_e32 v67, vcc, 0, v187, vcc
	global_load_dwordx4 v[162:165], v[66:67], off
	ds_read_b128 v[66:69], v206
	ds_read_b128 v[70:73], v206 offset:32
	ds_read_b128 v[74:77], v206 offset:64
	ds_read_b128 v[78:81], v206 offset:96
	ds_read_b128 v[166:169], v206 offset:128
	ds_read_b128 v[170:173], v206 offset:160
	ds_read_b128 v[174:177], v206 offset:192
	ds_read_b128 v[178:181], v206 offset:224
	s_waitcnt lgkmcnt(7)
	v_mfma_f32_32x32x16_bf16 v[82:97], v[66:69], v[142:145], 0
	s_waitcnt lgkmcnt(6)
	v_mfma_f32_32x32x16_bf16 v[82:97], v[70:73], v[138:141], v[82:97]
	s_waitcnt lgkmcnt(5)
	v_mfma_f32_32x32x16_bf16 v[82:97], v[74:77], v[134:137], v[82:97]
	s_waitcnt lgkmcnt(4)
	v_mfma_f32_32x32x16_bf16 v[82:97], v[78:81], v[130:133], v[82:97]
	ds_read_b128 v[66:69], v206 offset:256
	ds_read_b128 v[70:73], v206 offset:288
	ds_read_b128 v[74:77], v206 offset:320
	ds_read_b128 v[78:81], v206 offset:352
	s_waitcnt lgkmcnt(7)
	v_mfma_f32_32x32x16_bf16 v[82:97], v[166:169], v[126:129], v[82:97]
	s_waitcnt lgkmcnt(6)
	v_mfma_f32_32x32x16_bf16 v[82:97], v[170:173], v[122:125], v[82:97]
	s_waitcnt lgkmcnt(5)
	v_mfma_f32_32x32x16_bf16 v[82:97], v[174:177], v[118:121], v[82:97]
	s_waitcnt lgkmcnt(4)
	v_mfma_f32_32x32x16_bf16 v[82:97], v[178:181], v[114:117], v[82:97]
	ds_read_b128 v[166:169], v206 offset:12800
	ds_read_b128 v[170:173], v206 offset:12832
	ds_read_b128 v[174:177], v206 offset:12864
	ds_read_b128 v[178:181], v206 offset:12896
	s_waitcnt lgkmcnt(7)
	v_mfma_f32_32x32x16_bf16 v[82:97], v[66:69], v[110:113], v[82:97]
	ds_read_b128 v[194:197], v206 offset:12928
	ds_read_b128 v[198:201], v206 offset:12960
	ds_read_b128 v[218:221], v206 offset:12992
	ds_read_b128 v[222:225], v206 offset:13024
	s_waitcnt lgkmcnt(10)
	v_mfma_f32_32x32x16_bf16 v[82:97], v[70:73], v[106:109], v[82:97]
	s_waitcnt lgkmcnt(9)
	v_mfma_f32_32x32x16_bf16 v[82:97], v[74:77], v[102:105], v[82:97]
	s_waitcnt lgkmcnt(8)
	v_mfma_f32_32x32x16_bf16 v[82:97], v[78:81], v[98:101], v[82:97]
	s_waitcnt lgkmcnt(7)
	v_mfma_f32_32x32x16_bf16 v[66:81], v[166:169], v[142:145], 0
	s_waitcnt lgkmcnt(6)
	v_mfma_f32_32x32x16_bf16 v[66:81], v[170:173], v[138:141], v[66:81]
	s_waitcnt lgkmcnt(5)
	v_mfma_f32_32x32x16_bf16 v[66:81], v[174:177], v[134:137], v[66:81]
	s_waitcnt lgkmcnt(4)
	v_mfma_f32_32x32x16_bf16 v[66:81], v[178:181], v[130:133], v[66:81]
	ds_read_b128 v[166:169], v206 offset:13056
	ds_read_b128 v[170:173], v206 offset:13088
	ds_read_b128 v[174:177], v206 offset:13120
	ds_read_b128 v[178:181], v206 offset:13152
	s_waitcnt lgkmcnt(7)
	v_mfma_f32_32x32x16_bf16 v[66:81], v[194:197], v[126:129], v[66:81]
	s_waitcnt lgkmcnt(6)
	v_mfma_f32_32x32x16_bf16 v[66:81], v[198:201], v[122:125], v[66:81]
	s_waitcnt lgkmcnt(5)
	v_mfma_f32_32x32x16_bf16 v[66:81], v[218:221], v[118:121], v[66:81]
	s_waitcnt lgkmcnt(4)
	v_mfma_f32_32x32x16_bf16 v[66:81], v[222:225], v[114:117], v[66:81]
	s_waitcnt lgkmcnt(3)
	v_mfma_f32_32x32x16_bf16 v[66:81], v[166:169], v[110:113], v[66:81]
	v_add_u32_e32 v215, s31, v205
	s_waitcnt lgkmcnt(2)
	v_mfma_f32_32x32x16_bf16 v[66:81], v[170:173], v[106:109], v[66:81]
	s_waitcnt lgkmcnt(1)
	v_mfma_f32_32x32x16_bf16 v[66:81], v[174:177], v[102:105], v[66:81]
	s_waitcnt lgkmcnt(0)
	v_mfma_f32_32x32x16_bf16 v[66:81], v[178:181], v[98:101], v[66:81]
	ds_read_b128 v[178:181], v215 offset:25600
	ds_read_b128 v[174:177], v215 offset:30208
	ds_read_b128 v[166:169], v215 offset:34816
	ds_read_b128 v[170:173], v215 offset:39424
	v_max3_f32 v194, v82, v83, v84
	v_max3_f32 v195, v85, v86, v87
	v_max3_f32 v194, v194, v88, v89
	v_max3_f32 v195, v195, v90, v91
	v_max3_f32 v194, v194, v92, v93
	v_max3_f32 v195, v195, v94, v95
	v_max3_f32 v194, v194, v96, v97
	s_nop 1
	v_max3_f32 v195, v195, v66, v67
	v_max3_f32 v194, v194, v68, v69
	v_max3_f32 v195, v195, v70, v71
	v_max3_f32 v194, v194, v72, v73
	v_max3_f32 v195, v195, v74, v75
	v_max3_f32 v194, v194, v76, v77
	v_max3_f32 v195, v195, v78, v79
	v_max3_f32 v194, v194, v80, v81
	v_max_f32_e32 v214, v194, v195
	v_add_f32_e32 v194, 0x42800000, v216
	v_cmp_gt_f32_e32 vcc, v214, v194
	s_cbranch_vccz .LBB0_993
	v_mov_b32_e32 v194, v214
	s_nop 1
	v_permlane32_swap_b32_e32 v214, v194
	v_max3_f32 v214, v216, v214, v194
	v_sub_f32_e32 v194, v216, v214
	v_exp_f32_e32 v216, v194
	s_and_saveexec_b64 s[16:17], s[6:7]
	ds_write_b32 v191, v216
	s_or_b64 exec, exec, s[16:17]
	s_waitcnt lgkmcnt(0)
	v_add_u32_e32 v206, v183, v182
	v_mul_f32_e32 v192, v192, v216
	ds_read_b128 v[194:197], v206
	ds_read_b128 v[198:201], v206 offset:32
	ds_read_b128 v[216:219], v206 offset:64
	ds_read_b128 v[220:223], v206 offset:96
	s_waitcnt lgkmcnt(0)
	s_waitcnt lgkmcnt(3)
	v_pk_mul_f32 v[52:53], v[52:53], v[196:197]
	s_waitcnt lgkmcnt(2)
	v_pk_mul_f32 v[54:55], v[54:55], v[198:199]
	s_waitcnt lgkmcnt(1)
	v_pk_mul_f32 v[58:59], v[58:59], v[216:217]
	s_waitcnt lgkmcnt(0)
	v_pk_mul_f32 v[62:63], v[62:63], v[220:221]
	v_pk_mul_f32 v[64:65], v[64:65], v[222:223]
	v_pk_mul_f32 v[60:61], v[60:61], v[218:219]
	v_pk_mul_f32 v[56:57], v[56:57], v[200:201]
	v_pk_mul_f32 v[50:51], v[50:51], v[194:195]
	v_pk_mul_f32 v[46:47], v[46:47], v[220:221]
	v_pk_mul_f32 v[42:43], v[42:43], v[216:217]
	v_pk_mul_f32 v[38:39], v[38:39], v[198:199]
	v_pk_mul_f32 v[48:49], v[48:49], v[222:223]
	v_pk_mul_f32 v[44:45], v[44:45], v[218:219]
	v_pk_mul_f32 v[40:41], v[40:41], v[200:201]
	v_pk_mul_f32 v[36:37], v[36:37], v[196:197]
	v_pk_mul_f32 v[34:35], v[34:35], v[194:195]
	v_pk_mul_f32 v[30:31], v[30:31], v[220:221]
	v_pk_mul_f32 v[26:27], v[26:27], v[216:217]
	v_pk_mul_f32 v[22:23], v[22:23], v[198:199]
	v_pk_mul_f32 v[32:33], v[32:33], v[222:223]
	v_pk_mul_f32 v[28:29], v[28:29], v[218:219]
	v_pk_mul_f32 v[24:25], v[24:25], v[200:201]
	v_pk_mul_f32 v[20:21], v[20:21], v[196:197]
	v_pk_mul_f32 v[18:19], v[18:19], v[194:195]
	v_pk_mul_f32 v[14:15], v[14:15], v[220:221]
	v_pk_mul_f32 v[10:11], v[10:11], v[216:217]
	v_pk_mul_f32 v[6:7], v[6:7], v[198:199]
	v_pk_mul_f32 v[16:17], v[16:17], v[222:223]
	v_pk_mul_f32 v[12:13], v[12:13], v[218:219]
	v_pk_mul_f32 v[8:9], v[8:9], v[200:201]
	v_pk_mul_f32 v[4:5], v[4:5], v[196:197]
	v_pk_mul_f32 v[2:3], v[2:3], v[194:195]
	s_branch .LBB0_994
